# v5 plus P0 load balance: two-item waves spread over XCDs, gate-weight fold on single-item waves of every XCD
# baseline (speedup 1.0000x reference)
; #define LAS __attribute__((address_space(3)))
; __device__ __forceinline__ void p0_transposes(Frame& F, int it_lo, int it_hi, int gw, int NGW) {
;     int tx_ = (int)threadIdx.x; asm volatile("" : "+v"(tx_)); const int lane = tx_ & 63;
;     LAS float* scr = (LAS float*)(F.lds + RING_OFF + F.wave * 16384);
;     int it = it_lo + gw; if (it >= it_hi) return;
;     TrItem cur = tr_decode(F, it); f32x4 v[8]; float g[8];
; __device__ __forceinline__ void p0_prologue(Frame& F) {
;     const int gw = F.vcu * NWAVES + F.wave, NGW = F.G * NWAVES;
;     p0_transposes(F, 0, F.G == 256 ? P0_I_W1 : P0_NITEMS, gw, NGW);
;     for (int i = gw * 64 + F.lane; i < 16 * 1024; i += NGW * 64) { const int j = i >> 10, c = i & 1023;
.LBB0_6:
	s_or_b64 exec, exec, s[0:1]
	s_add_u32 s0, s88, 0x200000
	s_addc_u32 s1, s89, 0
	v_writelane_b32 v241, s0, 36
	s_movk_i32 s2, 0x980
	v_mov_b32_e32 v1, v0
	v_writelane_b32 v241, s1, 37
	s_add_u32 s0, s88, 0xc00000
	s_addc_u32 s1, s89, 0
	v_writelane_b32 v241, s0, 38
	s_nop 1
	v_writelane_b32 v241, s1, 39
	s_add_u32 s0, s88, 0xe00000
	s_addc_u32 s1, s89, 0
	s_add_u32 s94, s88, 0x1000000
	v_writelane_b32 v241, s0, 40
	s_addc_u32 s95, s89, 0
	s_nop 0
	v_writelane_b32 v241, s1, 41
	s_add_u32 s0, s88, 0x1800000
	s_addc_u32 s1, s89, 0
	v_writelane_b32 v241, s0, 42
	s_lshr_b32 s3, s4, 6
	s_lshl_b32 s92, s93, 3
	v_writelane_b32 v241, s1, 43
	s_lshl_b32 s0, s84, 3
	s_add_i32 s6, s0, s3
	s_cmpk_lg_i32 s93, 0x100
	s_cselect_b64 s[0:1], -1, 0
	v_writelane_b32 v241, s0, 44
	s_cmpk_eq_i32 s93, 0x100
	s_nop 0
	v_writelane_b32 v241, s1, 45
	s_cselect_b64 s[0:1], -1, 0
	v_writelane_b32 v241, s0, 46
	s_nop 1
	v_writelane_b32 v241, s1, 47
	s_and_b64 s[0:1], s[0:1], exec
	s_cselect_b32 s22, s2, 0x1d80
	s_lshl_b32 s0, s3, 14
	v_writelane_b32 v241, s3, 48
	s_add_i32 s0, s0, 0
	v_writelane_b32 v241, s0, 49
	s_mov_b32 s0, s6
	s_and_b32 s100, s6, 0xff
	s_lshl_b32 s100, s100, 3
	s_lshr_b32 vcc_lo, s6, 8
	s_or_b32 s100, s100, vcc_lo
	s_cmpk_eq_i32 s93, 0x100
	s_cselect_b32 s6, s100, s6
	s_cmp_ge_i32 s6, s22
	v_writelane_b32 v241, s0, 50
	s_nop 1
	v_writelane_b32 v241, s1, 51
	s_cbranch_scc1 .LBB0_109
	s_cmpk_gt_i32 s6, 0x97f
	s_cbranch_scc0 .LBB0_14
	s_cmpk_gt_u32 s6, 0xa7f
	s_cbranch_scc0 .LBB0_16
	s_cmpk_gt_u32 s6, 0xb7f
	s_cbranch_scc0 .LBB0_17
	s_cmpk_gt_u32 s6, 0xd7f
	s_cbranch_scc0 .LBB0_18
	s_lshl_b32 s4, s6, 5
	s_cmpk_gt_u32 s6, 0x157f
	s_cbranch_scc0 .LBB0_19
	v_readlane_b32 s36, v241, 18
	s_add_i32 s0, s6, 0xffffea80
	v_readlane_b32 s46, v241, 28
	v_readlane_b32 s47, v241, 29
	s_lshr_b32 s23, s0, 5
	s_and_b32 s24, s4, 0x3e0
	s_mov_b64 s[0:1], 0
	s_mov_b64 s[2:3], 0
	v_readlane_b32 s37, v241, 19
	v_readlane_b32 s38, v241, 20
	v_readlane_b32 s39, v241, 21
	v_readlane_b32 s40, v241, 22
	v_readlane_b32 s41, v241, 23
	v_readlane_b32 s42, v241, 24
	v_readlane_b32 s43, v241, 25
	v_readlane_b32 s44, v241, 26
	v_readlane_b32 s45, v241, 27
	v_readlane_b32 s48, v241, 30
	v_readlane_b32 s49, v241, 31
	v_readlane_b32 s50, v241, 32
	v_readlane_b32 s51, v241, 33
	s_mov_b64 s[6:7], s[46:47]
	s_branch .LBB0_20

; __device__ __forceinline__ unsigned f2bf(float f) { unsigned u = __builtin_bit_cast(unsigned, f); return (u + 0x7fffu + ((u >> 16) & 1u)) >> 16; }
; __device__ __forceinline__ void p0_prologue(Frame& F) {
;     ...
;     for (int i = gw * 64 + F.lane; i < 16 * 1024; i += NGW * 64) { const int j = i >> 10, c = i & 1023;
;         float v = 0.f;
;         if (j < 8) { const int cc = c & 511, g4 = cc >> 2, cj = cc & 3;
;             if (c < 512) { for (int ii = 0; ii < 4; ++ii) v += F.w_q_ml[(g4 * 4 + cj) * 4 + ii] * F.w_if[(4 * g4 + ii) * 8 + j] + F.w_k_ml[(g4 * 4 + cj) * 4 + ii] * F.w_if[(512 + 4 * g4 + ii) * 8 + j]; }
;             else { for (int ii = 0; ii < 4; ++ii) v += F.w_v_ml[(g4 * 4 + cj) * 4 + ii] * F.w_if[(1024 + 4 * g4 + ii) * 8 + j]; } }
;         F.Wif_t[i] = (bf16)f2bf(v); }
.LBB0_109:
	v_readlane_b32 s6, v241, 50
	s_nop 3
	s_and_b32 s100, s6, 0xff
	s_sub_i32 s100, s100, 48
	s_lshr_b32 vcc_lo, s6, 8
	s_lshl_b32 vcc_lo, vcc_lo, 5
	s_add_i32 vcc_lo, vcc_lo, s100
	s_cmp_lt_u32 s100, 32
	s_cselect_b32 s100, vcc_lo, 0x100
	s_cmpk_eq_i32 s93, 0x100
	s_cselect_b32 s100, s100, s6
	v_and_b32_e32 v6, 63, v0
	v_lshl_or_b32 v2, s100, 6, v6
	s_movk_i32 s0, 0x4000
	v_cmp_gt_i32_e32 vcc, s0, v2
	s_and_saveexec_b64 s[0:1], vcc
	s_cbranch_execz .LBB0_118
	s_lshl_b32 s2, s93, 9
	v_ashrrev_i32_e32 v3, 31, v2
	v_lshl_add_u64 v[4:5], v[2:3], 1, s[88:89]
	s_mov_b64 s[4:5], 0x23c0000
	s_ashr_i32 s3, s2, 31
	v_lshlrev_b32_e32 v1, 3, v2
	s_lshl_b32 s14, s93, 12
	v_lshlrev_b32_e32 v7, 2, v2
	s_lshl_b32 s15, s93, 11
	v_lshl_add_u64 v[4:5], v[4:5], 0, s[4:5]
	s_lshl_b64 s[4:5], s[2:3], 1
	s_mov_b64 s[6:7], 0
	s_movk_i32 s3, 0x2000
	s_mov_b64 s[8:9], 0x4000
	s_movk_i32 s16, 0x7fff
	s_movk_i32 s17, 0x3fff
	s_branch .LBB0_113
